# scan items pinned to blocks 0..63 (VGPR-staged pipelined scan), gridbar, remap613, fsub
# speedup vs baseline: 1.0105x; 1.0073x over previous
.LBB0_395:
	s_cmp_lt_i32 s38, 4
	s_cselect_b64 s[12:13], -1, 0
	s_and_b64 s[0:1], s[12:13], s[0:1]
	s_andn2_b64 vcc, exec, s[0:1]
	s_cbranch_vccnz .LBB0_494
	s_mov_b64 s[0:1], s[84:85]
	s_add_u32 s14, s0, 0x2ce10000
	s_addc_u32 s15, s1, 0
	v_mbcnt_lo_u32_b32 v1, -1, 0
	s_add_u32 s16, s0, 0x2d500120
	v_mbcnt_hi_u32_b32 v202, -1, v1
	s_addc_u32 s17, s1, 0
	s_add_i32 s2, 0, 0x11ff0
	v_and_b32_e32 v1, 64, v202
	v_and_b32_e32 v198, 0x3ff, v0
	s_mov_b32 s19, 0
	v_mov_b32_e32 v199, 1
	v_mov_b32_e32 v200, s2
	s_movk_i32 s3, 0x103f
	s_mov_b64 s[20:21], 0x4000000
	v_mov_b32_e32 v3, 0
	s_movk_i32 s25, 0x1c00
	s_mov_b64 s[22:23], 0x2cc00000
	s_add_i32 s33, 0, 0x11a00
	s_mov_b32 s36, 0x2d600000
	s_mov_b32 s37, 0xf800000
	v_mov_b32_e32 v201, 0x260
	s_mov_b32 s24, 0x3e38aa3b
	s_mov_b64 s[26:27], 0x20000000
	s_mov_b64 s[28:29], 0x20080000
	s_movk_i32 s41, 0x90
	s_mov_b64 s[30:31], 0x24000000
	s_mov_b64 s[34:35], 0x2e000000
	s_mov_b64 s[44:45], 0x2e008000
	s_mov_b64 s[46:47], 0xe000
	s_mov_b32 s42, 0x2e01a000
	s_movk_i32 s43, 0x7fff
	s_brev_b32 s60, 32
	s_mov_b32 s61, 0x4002000
	s_mov_b32 s62, 0x4004000
	s_mov_b32 s63, 0x4006000
	s_mov_b32 s64, 0x401c000
	s_mov_b32 s65, 0x401e000
	s_mov_b32 s66, 0x4020000
	s_mov_b32 s67, 0x4022000
	s_mov_b32 s68, 0x4038000
	s_mov_b32 s69, 0x403a000
	s_mov_b32 s70, 0x403c000
	s_mov_b32 s71, 0x403e000
	s_mov_b32 s72, 0x4054000
	s_mov_b32 s73, 0x4056000
	s_mov_b32 s74, 0x4058000
	s_mov_b64 s[48:49], 0x70000
	s_mov_b64 s[50:51], 0x12000
	v_xor_b32_e32 v203, 16, v202
	v_add_u32_e32 v204, 64, v1
	v_xor_b32_e32 v205, 32, v202
	v_xor_b32_e32 v206, 8, v202
	v_xor_b32_e32 v207, 4, v202
	v_xor_b32_e32 v208, 2, v202
	v_xor_b32_e32 v209, 1, v202
	v_mov_b32_e32 v156, 0xf149f2ca
	v_mov_b32_e32 v210, 0x12000
	s_cmpk_lt_u32 s82, 0x40
	s_cselect_b32 s32, 1, 0
	s_branch .LBB0_399

.LBB0_399:
	v_mov_b32_e32 v1, v198
	s_waitcnt lgkmcnt(0)
	s_barrier
	s_nop 0
	v_cmp_eq_u32_e32 vcc, 0, v1
	s_and_saveexec_b64 s[0:1], vcc
	s_cbranch_execz .LBB0_401
	s_cmp_lg_u32 s32, 0
	s_cbranch_scc1 .Lscan_direct
	v_mov_b64_e32 v[4:5], s[14:15]
	flat_atomic_add v1, v[4:5], v199 sc0
	v_mov_b32_e32 v2, s2
	s_waitcnt vmcnt(0) lgkmcnt(0)
	v_add_u32_e32 v1, 64, v1
	s_branch .Lscan_wr
.Lscan_direct:
	s_mov_b32 s32, 0
	v_mov_b32_e32 v1, s82
	v_mov_b32_e32 v2, s2
.Lscan_wr:
	ds_write_b32 v2, v1
